# barrier: invalidate hoist + drop the leader's two vmcnt(0) waits around the fire-and-forget release atomic
# speedup vs baseline: 1.0035x; 1.0035x over previous
.LBB0_275:
	s_or_b64 exec, exec, s[6:7]
	s_mov_b64 s[6:7], exec
	v_mbcnt_lo_u32_b32 v0, s6, 0
	v_mbcnt_hi_u32_b32 v0, s7, v0
	v_cmp_eq_u32_e32 vcc, 0, v0
	s_and_saveexec_b64 s[10:11], vcc
	s_cbranch_execz .LBB0_277
	s_bcnt1_i32_b64 s6, s[6:7]
	v_mov_b32_e32 v0, 0x2000
	v_mov_b32_e32 v1, s6
	global_atomic_add v0, v1, s[4:5] offset:1024
.LBB0_277:
	s_or_b64 exec, exec, s[10:11]
.LBB0_278:
	s_or_b64 exec, exec, s[0:1]
	s_waitcnt lgkmcnt(0)
	s_barrier
	v_mbcnt_lo_u32_b32 v0, -1, 0
	v_mbcnt_hi_u32_b32 v0, -1, v0
	s_cmpk_lt_i32 s2, 0x80
	v_add_u32_e32 v8, s33, v0
	s_cselect_b64 s[0:1], -1, 0
	s_cmpk_gt_i32 s2, 0x7f
	v_readfirstlane_b32 s8, v8
	s_cbranch_scc1 .LBB0_284
	s_ashr_i32 s4, s2, 31
	s_lshr_b32 s4, s4, 29
	s_add_i32 s6, s2, s4
	s_and_b32 s4, s6, -8
	s_sub_i32 s7, s2, s4
	s_cmp_gt_i32 s7, -1
	s_cbranch_scc0 .LBB0_281
	s_lshl_b32 s9, s7, 4
	s_cbranch_execz .LBB0_282
	s_branch .LBB0_283

.LBB0_430:
	s_or_b64 exec, exec, s[10:11]
.LBB0_431:
	s_or_b64 exec, exec, s[0:1]
	s_add_u32 s10, s26, 0x4900000
	s_addc_u32 s11, s27, 0
	s_movk_i32 s0, 0x100
	s_add_u32 s14, s26, 0x5600000
	s_waitcnt lgkmcnt(0)
	s_barrier
	s_addc_u32 s15, s27, 0
	v_mbcnt_lo_u32_b32 v0, -1, 0
	v_mbcnt_hi_u32_b32 v0, -1, v0
	s_cmpk_gt_i32 s2, 0xbf
	v_add_u32_e32 v12, s33, v0
	s_nop 0
	v_readfirstlane_b32 s5, v12
	s_cbranch_scc1 .LBB0_452
	v_lshlrev_b32_e32 v0, 4, v12
	v_add_u32_e32 v1, 0x2000, v0
	v_ashrrev_i32_e32 v2, 31, v1
	v_lshrrev_b32_e32 v2, 22, v2
	v_add_u32_e32 v2, v1, v2
	v_ashrrev_i32_e32 v2, 10, v2
	v_mul_i32_i24_e32 v3, 0x400, v2
	v_sub_u32_e32 v1, v1, v3
	v_lshrrev_b32_e32 v3, 4, v1
	v_bitop3_b32 v1, v3, v1, 32 bitop3:0x6c
	v_ashrrev_i32_e32 v3, 31, v1
	v_lshrrev_b32_e32 v3, 26, v3
	v_add_u32_e32 v3, v1, v3
	v_lshlrev_b32_e32 v5, 3, v2
	v_ashrrev_i32_e32 v4, 6, v3
	v_and_b32_e32 v5, -16, v5
	v_lshlrev_b32_e32 v2, 5, v2
	v_add_u32_e32 v5, v4, v5
	v_and_b32_e32 v13, 32, v2
	v_and_b32_e32 v2, 0xc0, v3
	v_and_b32_e32 v4, 3, v4
	s_mov_b32 s4, 0x7fffffe0
	v_lshrrev_b32_e32 v6, 2, v5
	v_lshlrev_b32_e32 v7, 1, v5
	v_sub_u32_e32 v1, v1, v2
	v_mov_b32_e32 v2, 1
	v_and_or_b32 v4, v5, s4, v4
	v_and_b32_e32 v6, 4, v6
	v_and_b32_e32 v7, 24, v7
	v_ashrrev_i16_sdwa v1, v2, sext(v1) dst_sel:DWORD dst_unused:UNUSED_PAD src0_sel:DWORD src1_sel:BYTE_0
	v_or3_b32 v4, v4, v6, v7
	v_bfe_i32 v14, v1, 0, 16
	v_mul_lo_u32 v4, v4, s0
	v_add_u32_e32 v1, v13, v14
	v_mul_lo_u32 v15, v5, s0
	v_add_lshl_u32 v128, v4, v1, 1
	v_add_lshl_u32 v130, v1, v15, 1
	v_bfe_i32 v1, v12, 27, 1
	v_lshrrev_b32_e32 v1, 22, v1
	v_add_u32_e32 v1, v0, v1
	v_and_b32_e32 v1, 0xfffffc00, v1
	v_sub_u32_e32 v0, v0, v1
	v_lshrrev_b32_e32 v1, 4, v0
	v_ashrrev_i32_e32 v4, 31, v12
	v_bitop3_b32 v0, v1, v0, 32 bitop3:0x6c
	v_lshrrev_b32_e32 v4, 26, v4
	v_ashrrev_i32_e32 v1, 31, v0
	v_add_u32_e32 v4, v12, v4
	v_lshrrev_b32_e32 v1, 26, v1
	v_ashrrev_i32_e32 v4, 6, v4
	v_add_u32_e32 v1, v0, v1
	v_lshlrev_b32_e32 v5, 3, v4
	s_add_u32 s35, s26, 0x2080000
	v_ashrrev_i32_e32 v3, 6, v1
	v_and_b32_e32 v5, -16, v5
	s_addc_u32 s48, s27, 0
	v_add_u32_e32 v5, v3, v5
	v_and_b32_e32 v3, 3, v3
	s_ashr_i32 s8, s2, 31
	v_and_or_b32 v3, v5, s4, v3
	s_lshr_b32 s4, s8, 29
	s_add_i32 s4, s2, s4
	s_ashr_i32 s6, s5, 6
	s_ashr_i32 s1, s0, 31
	s_ashr_i32 s9, s4, 3
	s_and_b32 s4, s4, -8
	s_ashr_i32 s7, s5, 8
	s_lshl_b64 s[12:13], s[0:1], 8
	s_lshl_b64 s[16:17], s[0:1], 9
	s_lshl_b32 s49, s6, 10
	s_sub_i32 s4, s2, s4
	s_cmp_lt_i32 s4, 0
	s_cselect_b32 s18, 25, 24
	s_mul_i32 s4, s4, s18
	s_add_i32 s4, s4, s9
	s_mul_hi_i32 s9, s4, 0x2aaaaaab
	s_lshr_b32 s18, s9, 31
	s_ashr_i32 s9, s9, 1
	s_add_i32 s9, s9, s18
	s_lshl_b32 s18, s9, 2
	s_mul_i32 s9, s9, 12
	s_sub_i32 s9, s4, s9
	s_bfe_i32 s4, s9, 0x80000
	s_bfe_u32 s4, s4, 0x2000d
	s_add_i32 s19, s9, s4
	s_bfe_i32 s4, s19, 0x80000
	s_and_b32 s19, s19, 0xfc
	s_sub_i32 s9, s9, s19
	s_sext_i32_i8 s9, s9
	s_add_i32 s67, s18, s9
	s_ashr_i32 s9, s67, 31
	s_mul_i32 s9, s16, s9
	s_mul_hi_u32 s18, s16, s67
	s_sext_i32_i16 s22, s4
	s_add_i32 s9, s18, s9
	s_lshr_b64 s[18:19], s[0:1], 23
	s_lshr_b32 s4, s22, 2
	s_mul_i32 s19, s18, s67
	s_add_i32 s23, s9, s19
	s_bfe_i64 s[20:21], s[4:5], 0x100000
	s_ashr_i32 s9, s22, 2
	v_and_b32_e32 v1, 0xc0, v1
	s_mul_hi_u32 s19, s16, s9
	s_mul_i32 s20, s16, s21
	v_lshrrev_b32_e32 v6, 2, v5
	v_lshlrev_b32_e32 v7, 1, v5
	v_sub_u32_e32 v0, v0, v1
	s_add_i32 s19, s19, s20
	s_mul_i32 s18, s18, s9
	v_and_b32_e32 v6, 4, v6
	v_and_b32_e32 v7, 24, v7
	v_lshlrev_b32_e32 v4, 5, v4
	v_ashrrev_i16_sdwa v0, v2, sext(v0) dst_sel:DWORD dst_unused:UNUSED_PAD src0_sel:DWORD src1_sel:BYTE_0
	s_add_i32 s19, s19, s18
	s_mul_i32 s9, s16, s9
	v_or3_b32 v3, v3, v6, v7
	v_and_b32_e32 v16, 32, v4
	v_bfe_i32 v17, v0, 0, 16
	s_add_u32 s42, s35, s9
	v_mul_lo_u32 v3, v3, s0
	v_add_u32_e32 v0, v16, v17
	s_addc_u32 s43, s48, s19
	s_add_i32 s9, s49, 0
	v_add_lshl_u32 v132, v3, v0, 1
	s_add_i32 m0, s9, 0x10000
	s_mul_i32 s38, s16, s67
	global_load_lds_dwordx4 v132, s[42:43]
	s_add_i32 m0, s9, 0x12000
	s_add_u32 s18, s42, s12
	global_load_lds_dwordx4 v128, s[42:43]
	s_addc_u32 s19, s43, s13
	s_add_i32 m0, s9, 0x14000
	v_mul_lo_u32 v18, v5, s0
	global_load_lds_dwordx4 v132, s[18:19]
	s_add_i32 m0, s9, 0x16000
	s_add_u32 s40, s10, s38
	s_addc_u32 s41, s11, s23
	s_add_i32 s54, s9, 0x2000
	v_add_lshl_u32 v134, v0, v18, 1
	global_load_lds_dwordx4 v128, s[18:19]
	s_mov_b32 m0, s9
	s_add_u32 s20, s40, s12
	global_load_lds_dwordx4 v134, s[40:41]
	s_mov_b32 m0, s54
	s_addc_u32 s21, s41, s13
	s_add_i32 s55, s9, 0x4000
	global_load_lds_dwordx4 v130, s[40:41]
	s_mov_b32 m0, s55
	s_add_i32 s56, s9, 0x6000
	global_load_lds_dwordx4 v134, s[20:21]
	s_mov_b32 m0, s56
	v_mov_b32_e32 v133, 0
	global_load_lds_dwordx4 v130, s[20:21]
	v_mov_b32_e32 v129, v133
	v_mov_b32_e32 v135, v133
	v_mov_b32_e32 v131, v133
	s_cmp_eq_u32 s7, 1
	s_mov_b32 s57, 0
	v_lshl_add_u64 v[8:9], s[42:43], 0, v[132:133]
	v_lshl_add_u64 v[4:5], s[42:43], 0, v[128:129]
	v_lshl_add_u64 v[2:3], s[18:19], 0, v[132:133]
	v_lshl_add_u64 v[0:1], s[18:19], 0, v[128:129]
	v_lshl_add_u64 v[6:7], s[40:41], 0, v[134:135]
	s_cselect_b64 s[18:19], -1, 0
	s_cmp_lg_u32 s7, 1
	v_lshl_add_u64 v[10:11], s[40:41], 0, v[130:131]
	s_cbranch_scc1 .LBB0_434
	s_barrier

.LBB0_530:
	s_or_b64 exec, exec, s[6:7]
	s_mov_b64 s[6:7], exec
	v_mbcnt_lo_u32_b32 v0, s6, 0
	v_mbcnt_hi_u32_b32 v0, s7, v0
	v_cmp_eq_u32_e32 vcc, 0, v0
	s_and_saveexec_b64 s[12:13], vcc
	s_cbranch_execz .LBB0_532
	s_bcnt1_i32_b64 s6, s[6:7]
	v_mov_b32_e32 v0, 0x2000
	v_mov_b32_e32 v1, s6
	global_atomic_add v0, v1, s[4:5] offset:1024
.LBB0_532:
	s_or_b64 exec, exec, s[12:13]
.LBB0_533:
	s_or_b64 exec, exec, s[0:1]
	s_add_u32 s0, s26, 0x8e00000
	s_addc_u32 s1, s27, 0
	s_add_u32 s6, s26, 0xa600000
	s_addc_u32 s7, s27, 0
	s_add_u32 s12, s26, 0xbe00000
	s_waitcnt lgkmcnt(0)
	v_cndmask_b32_e64 v0, 0, 1, s[20:21]
	s_addc_u32 s13, s27, 0
	v_cmp_ne_u32_e64 s[4:5], 1, v0
	s_andn2_b64 vcc, exec, s[20:21]
	s_barrier
	v_mbcnt_lo_u32_b32 v0, -1, 0
	v_mbcnt_hi_u32_b32 v0, -1, v0
	s_cbranch_vccnz .LBB0_536
	s_add_u32 s20, s26, 0x5500000
	v_and_b32_e32 v218, 7, v0
	s_addc_u32 s21, s27, 0
	v_add_u32_e32 v1, s33, v0
	v_mul_u32_u24_e32 v0, 0x60, v218
	s_add_u32 s22, s26, 0x2600000
	v_lshlrev_b32_e32 v100, 1, v0
	v_mov_b32_e32 v101, 0
	s_addc_u32 s23, s27, 0
	v_lshl_add_u64 v[102:103], s[14:15], 0, v[100:101]
	v_lshlrev_b32_e32 v100, 8, v218
	s_add_u32 s38, s26, 0x2700000
	v_ashrrev_i32_e32 v2, 3, v1
	v_lshl_add_u64 v[104:105], s[18:19], 0, v[100:101]
	v_lshlrev_b32_e32 v100, 5, v218
	v_lshlrev_b32_e32 v0, 6, v218
	v_mov_b32_e32 v1, v101
	s_mov_b32 s14, 0x3c2aaaab
	s_addc_u32 s39, s27, 0
	v_lshl_add_u64 v[106:107], s[10:11], 0, v[0:1]
	v_lshl_add_u64 v[108:109], s[16:17], 0, v[100:101]
	v_lshl_add_u32 v110, s2, 6, v2
	s_lshl_b32 s16, s28, 6
	s_movk_i32 s17, 0x1fff
	s_movk_i32 s18, 0x600
	v_mov_b32_e32 v100, 0x358637bd
	s_mov_b32 s19, 0x800000
	s_movk_i32 s35, 0xc0
	v_mov_b64_e32 v[112:113], s[0:1]
	s_brev_b32 s15, 60
	v_mov_b64_e32 v[114:115], s[6:7]
	s_mov_b32 s40, s2

.LBB0_585:
	s_or_b64 exec, exec, s[18:19]
	s_mov_b64 s[18:19], exec
	v_mbcnt_lo_u32_b32 v0, s18, 0
	v_mbcnt_hi_u32_b32 v0, s19, v0
	v_cmp_eq_u32_e32 vcc, 0, v0
	s_and_saveexec_b64 s[20:21], vcc
	s_cbranch_execz .LBB0_587
	s_bcnt1_i32_b64 s8, s[18:19]
	v_mov_b32_e32 v0, 0x2000
	v_mov_b32_e32 v1, s8
	global_atomic_add v0, v1, s[16:17] offset:1024
.LBB0_587:
	s_or_b64 exec, exec, s[20:21]
.LBB0_588:
	s_or_b64 exec, exec, s[14:15]
	s_mov_b64 s[14:15], 0
	s_waitcnt lgkmcnt(0)
	v_mov_b32_e32 v0, 0
	v_mov_b32_e32 v1, 0
	v_mov_b32_e32 v2, 0
	s_barrier

.LBB0_743:
	s_or_b64 exec, exec, s[12:13]
	s_mov_b64 s[12:13], exec
	v_mbcnt_lo_u32_b32 v0, s12, 0
	v_mbcnt_hi_u32_b32 v0, s13, v0
	v_cmp_eq_u32_e32 vcc, 0, v0
	s_and_saveexec_b64 s[16:17], vcc
	s_cbranch_execz .LBB0_745
	s_bcnt1_i32_b64 s8, s[12:13]
	v_mov_b32_e32 v0, 0x2000
	v_mov_b32_e32 v1, s8
	global_atomic_add v0, v1, s[6:7] offset:1024
.LBB0_745:
	s_or_b64 exec, exec, s[16:17]
.LBB0_746:
	s_or_b64 exec, exec, s[0:1]
	s_add_u32 s12, s26, 0x6900000
	s_addc_u32 s13, s27, 0
	s_cmpk_lt_i32 s2, 0x400
	s_cselect_b64 s[6:7], -1, 0
	s_cmpk_gt_i32 s2, 0x3ff
	s_waitcnt lgkmcnt(0)
	s_barrier
	v_mbcnt_lo_u32_b32 v0, -1, 0
	v_mbcnt_hi_u32_b32 v0, -1, v0
	s_cbranch_scc1 .LBB0_753
	s_add_u32 s16, s26, 0x5900000
	s_addc_u32 s17, s27, 0
	s_ashr_i32 s0, s2, 9
	s_ashr_i32 s1, s0, 31
	s_lshl_b64 s[18:19], s[0:1], 13
	s_lshl_b32 s0, s2, 7
	v_add_u32_e32 v1, s33, v0
	s_bfe_u32 s20, s2, 0x30006
	s_and_b32 s0, s0, 0x1f80
	v_ashrrev_i32_e32 v66, 3, v1
	s_or_b32 s18, s18, s0
	s_lshl_b32 s0, s20, 7
	v_ashrrev_i32_e32 v67, 31, v66
	s_add_u32 s8, s16, s0
	v_lshlrev_b32_e32 v4, 4, v0
	v_lshl_add_u64 v[2:3], s[18:19], 0, v[66:67]
	s_addc_u32 s9, s17, 0
	v_and_b32_e32 v4, 0x70, v4
	v_mov_b32_e32 v5, 0
	v_lshl_add_u64 v[6:7], s[8:9], 0, v[4:5]
	v_lshlrev_b64 v[2:3], 10, v[2:3]
	v_lshl_add_u64 v[2:3], v[6:7], 0, v[2:3]
	s_mov_b32 s8, 0x10000
	v_and_b32_e32 v64, 0x7f, v1
	v_add_co_u32_e32 v6, vcc, s8, v2
	v_ashrrev_i32_e32 v8, 7, v1
	s_nop 0
	v_addc_co_u32_e32 v7, vcc, 0, v3, vcc
	global_load_dwordx4 v[32:35], v[2:3], off
	global_load_dwordx4 v[36:39], v[6:7], off
	v_or_b32_e32 v2, s18, v64
	v_mov_b32_e32 v3, s19
	v_lshlrev_b64 v[2:3], 11, v[2:3]
	s_mov_b32 s1, 0
	v_lshl_add_u64 v[2:3], s[12:13], 0, v[2:3]
	s_lshl_b32 s0, s20, 8
	v_lshlrev_b32_e32 v68, 3, v8
	v_lshl_add_u64 v[2:3], v[2:3], 0, s[0:1]
	v_ashrrev_i32_e32 v69, 31, v68
	v_lshl_add_u64 v[2:3], v[68:69], 1, v[2:3]
	global_load_dwordx4 v[40:43], v[2:3], off
	global_load_dwordx4 v[44:47], v[2:3], off offset:64
	global_load_dwordx4 v[48:51], v[2:3], off offset:128
	global_load_dwordx4 v[52:55], v[2:3], off offset:192
	v_and_b32_e32 v2, 0x73, v1
	v_lshrrev_b32_e32 v1, 1, v1
	v_lshlrev_b32_e32 v6, 1, v0
	v_and_b32_e32 v3, 4, v1
	v_and_b32_e32 v6, 8, v6
	v_and_b32_e32 v7, 31, v0
	v_and_b32_e32 v1, 0x60, v1
	v_or3_b32 v2, v2, v3, v6
	v_bfe_u32 v6, v0, 5, 1
	v_or_b32_e32 v0, v1, v7
	v_add_u32_e32 v9, 0, v4
	v_lshl_add_u64 v[70:71], s[16:17], 0, v[4:5]
	v_mul_u32_u24_e32 v10, 0x110, v0
	v_and_b32_e32 v0, 0xffffffe0, v66
	v_lshlrev_b32_e32 v4, 7, v1
	v_lshl_add_u32 v65, v2, 1, 0
	v_lshl_add_u64 v[2:3], s[26:27], 0, v[4:5]
	v_ashrrev_i32_e32 v1, 31, v0
	v_lshl_add_u64 v[0:1], v[0:1], 1, v[2:3]
	v_lshlrev_b32_e32 v4, 1, v7
	v_lshl_add_u64 v[0:1], v[0:1], 0, v[4:5]
	v_lshlrev_b32_e32 v2, 9, v6
	v_mov_b32_e32 v3, v5
	v_lshlrev_b32_e32 v11, 4, v6
	v_lshl_add_u64 v[0:1], v[0:1], 0, v[2:3]
	s_mov_b64 s[16:17], 0xa900000
	s_movk_i32 s0, 0x90
	v_lshl_add_u64 v[72:73], v[0:1], 0, s[16:17]
	v_add3_u32 v0, v10, v11, 0
	v_mul_lo_u32 v7, v66, s0
	s_movk_i32 s0, 0x880
	v_add_u32_e32 v76, 0x4800, v0
	v_lshlrev_b32_e32 v0, 1, v66
	v_mul_lo_u32 v75, v8, s0
	v_and_b32_e32 v0, 0xffffffc0, v0
	s_movk_i32 s0, 0x240
	v_mad_u32_u24 v0, v6, s0, v0
	v_lshlrev_b32_e32 v74, 2, v6
	v_add_u32_e32 v8, 0x2200, v75
	v_or_b32_e32 v0, v0, v4
	v_xor_b32_e32 v77, 0x64, v74
	v_add_u32_e32 v78, 0, v0
	v_add_u32_e32 v79, v9, v7
	v_add_u32_e32 v80, v65, v8
	s_mov_b32 s9, 0x3fb8aa3b
	s_mov_b32 s20, 0xc2ce8ed0
	s_mov_b32 s21, 0x42b17218
	v_mov_b32_e32 v81, 0x7f800000
	s_mov_b32 s16, s2

.LBB0_804:
	s_or_b64 exec, exec, s[20:21]
.LBB0_805:
	s_or_b64 exec, exec, s[0:1]
	s_add_u32 s18, s26, 0xa900000
	s_addc_u32 s19, s27, 0
	s_add_i32 s0, s33, s3
	s_waitcnt lgkmcnt(0)
	s_barrier
	v_mbcnt_lo_u32_b32 v0, -1, 0
	v_mbcnt_hi_u32_b32 v0, -1, v0
	s_nop 0
	v_add_u32_e32 v4, s0, v0
	s_mov_b32 s0, 0x40000
	v_cmp_gt_i32_e32 vcc, s0, v4
	s_and_saveexec_b64 s[16:17], vcc
	s_cbranch_execz .LBB0_810
	s_mov_b64 s[20:21], 0
	s_mov_b32 s3, 0x20000
	v_mov_b32_e32 v5, s53
	v_mov_b32_e32 v6, s51
	v_mov_b32_e32 v7, s52
	v_mov_b32_e32 v8, s50
	v_mov_b32_e32 v1, 0
	s_mov_b32 s8, 0x3fb8aa3b
	s_mov_b32 s9, 0xc2ce8ed0
	s_mov_b32 s22, 0x42b17218
	v_mov_b32_e32 v9, 0x7f800000
	s_mov_b32 s23, 0x3fffff0
	s_mov_b32 s35, 0x3ffff

.LBB0_859:
	s_or_b64 exec, exec, s[20:21]
	s_mov_b64 s[20:21], exec
	v_mbcnt_lo_u32_b32 v0, s20, 0
	v_mbcnt_hi_u32_b32 v0, s21, v0
	v_cmp_eq_u32_e32 vcc, 0, v0
	s_and_saveexec_b64 s[22:23], vcc
	s_cbranch_execz .LBB0_861
	s_bcnt1_i32_b64 s3, s[20:21]
	v_mov_b32_e32 v0, 0x2000
	v_mov_b32_e32 v1, s3
	global_atomic_add v0, v1, s[16:17] offset:1024
.LBB0_861:
	s_or_b64 exec, exec, s[22:23]
.LBB0_862:
	s_or_b64 exec, exec, s[0:1]
	s_add_u32 s16, s26, 0xde00000
	s_addc_u32 s17, s27, 0
	s_add_u32 s20, s26, 0x8900000
	s_addc_u32 s21, s27, 0
	s_andn2_b64 vcc, exec, s[6:7]
	s_waitcnt lgkmcnt(0)
	s_barrier
	v_mbcnt_lo_u32_b32 v0, -1, 0
	v_mbcnt_hi_u32_b32 v0, -1, v0
	s_cbranch_vccnz .LBB0_871
	s_add_u32 s6, s26, 0x5900000
	s_addc_u32 s7, s27, 0
	s_ashr_i32 s0, s2, 9
	s_and_b32 s3, s2, 63
	s_ashr_i32 s1, s0, 31
	v_add_u32_e32 v1, s33, v0
	s_bfe_u32 s34, s2, 0x30006
	s_lshl_b64 s[8:9], s[0:1], 13
	s_lshl_b32 s0, s3, 7
	v_ashrrev_i32_e32 v106, 3, v1
	s_or_b32 s8, s8, s0
	s_lshl_b32 s0, s34, 7
	v_ashrrev_i32_e32 v107, 31, v106
	s_add_u32 s22, s6, s0
	v_lshlrev_b32_e32 v4, 4, v0
	v_lshl_add_u64 v[2:3], s[8:9], 0, v[106:107]
	s_addc_u32 s23, s7, 0
	v_and_b32_e32 v108, 0x70, v4
	v_mov_b32_e32 v109, 0
	v_lshl_add_u64 v[4:5], s[22:23], 0, v[108:109]
	v_lshlrev_b64 v[2:3], 10, v[2:3]
	v_lshl_add_u64 v[2:3], v[4:5], 0, v[2:3]
	s_mov_b32 s23, 0x10000
	v_and_b32_e32 v104, 0x7f, v1
	v_add_co_u32_e32 v4, vcc, s23, v2
	v_ashrrev_i32_e32 v12, 7, v1
	s_nop 0
	v_addc_co_u32_e32 v5, vcc, 0, v3, vcc
	global_load_dwordx4 v[48:51], v[2:3], off
	global_load_dwordx4 v[52:55], v[4:5], off
	v_or_b32_e32 v2, s8, v104
	v_mov_b32_e32 v3, s9
	v_lshlrev_b64 v[2:3], 11, v[2:3]
	s_mov_b32 s1, 0
	v_lshl_add_u64 v[2:3], s[12:13], 0, v[2:3]
	s_lshl_b32 s0, s34, 8
	v_lshlrev_b32_e32 v110, 3, v12
	s_ashr_i32 s3, s2, 31
	v_lshl_add_u64 v[2:3], v[2:3], 0, s[0:1]
	v_ashrrev_i32_e32 v111, 31, v110
	s_lshl_b64 s[8:9], s[2:3], 14
	v_lshl_add_u64 v[2:3], v[110:111], 1, v[2:3]
	s_add_u32 s8, s18, s8
	global_load_dwordx4 v[56:59], v[2:3], off
	global_load_dwordx4 v[60:63], v[2:3], off offset:64
	global_load_dwordx4 v[64:67], v[2:3], off offset:128
	global_load_dwordx4 v[68:71], v[2:3], off offset:192
	s_addc_u32 s9, s19, s9
	s_add_i32 s34, s2, 0x400
	v_lshlrev_b32_e32 v2, 6, v106
	s_ashr_i32 s35, s34, 31
	v_ashrrev_i32_e32 v3, 31, v2
	s_lshl_b64 s[34:35], s[34:35], 14
	v_lshlrev_b64 v[112:113], 1, v[2:3]
	v_add_u32_e32 v2, 0x1000, v2
	s_add_u32 s34, s18, s34
	v_ashrrev_i32_e32 v3, 31, v2
	s_addc_u32 s35, s19, s35
	v_lshl_add_u64 v[4:5], s[8:9], 0, v[108:109]
	v_lshlrev_b64 v[114:115], 1, v[2:3]
	v_lshl_add_u64 v[6:7], s[34:35], 0, v[108:109]
	v_lshl_add_u64 v[8:9], v[4:5], 0, v[112:113]
	v_lshl_add_u64 v[2:3], v[4:5], 0, v[114:115]
	v_lshl_add_u64 v[10:11], v[6:7], 0, v[112:113]
	global_load_dwordx4 v[72:75], v[8:9], off
	global_load_dwordx4 v[76:79], v[10:11], off
	v_lshl_add_u64 v[4:5], v[6:7], 0, v[114:115]
	global_load_dwordx4 v[80:83], v[2:3], off
	global_load_dwordx4 v[84:87], v[4:5], off
	v_lshrrev_b32_e32 v3, 1, v0
	v_lshlrev_b32_e32 v4, 1, v0
	v_and_b32_e32 v2, 0x73, v1
	v_and_b32_e32 v3, 4, v3
	v_and_b32_e32 v4, 8, v4
	v_ashrrev_i32_e32 v5, 6, v1
	v_ashrrev_i32_e32 v1, 2, v1
	v_or3_b32 v2, v2, v3, v4
	v_and_b32_e32 v4, 31, v0
	v_and_b32_e32 v10, 0xffffffc0, v1
	v_or_b32_e32 v11, v10, v4
	s_movk_i32 s8, 0x90
	s_add_i32 s3, 0, 0x11800
	v_mul_lo_u32 v11, v11, s8
	v_add_u32_e32 v8, s3, v108
	v_lshl_add_u32 v105, v2, 1, 0
	v_lshlrev_b32_e32 v2, 5, v5
	v_add_u32_e32 v13, 0, v11
	v_add_u32_e32 v11, s3, v11
	s_movk_i32 s3, 0x80
	s_add_i32 s0, 0, 0x16000
	v_and_b32_e32 v9, 0x60, v2
	v_bitop3_b32 v2, v2, s3, v4 bitop3:0x36
	v_lshl_add_u32 v6, v4, 2, s0
	v_lshl_add_u32 v130, v2, 2, s0
	s_movk_i32 s0, 0x880
	v_or_b32_e32 v120, v9, v4
	v_mul_lo_u32 v131, v12, s0
	v_lshrrev_b32_e32 v1, 6, v1
	s_movk_i32 s0, 0x4400
	v_bfe_u32 v3, v0, 5, 1
	v_add_u32_e32 v15, 1, v120
	v_mul_lo_u32 v1, v1, s0
	s_movk_i32 s0, 0x110
	v_lshlrev_b32_e32 v14, 4, v3
	v_cvt_f32_ubyte0_e32 v122, v15
	v_mul_u32_u24_e32 v15, 0x90, v4
	v_mad_u32_u24 v1, v4, s0, v1
	v_add_u32_e32 v7, 0, v108
	v_lshl_add_u64 v[116:117], s[6:7], 0, v[108:109]
	v_lshlrev_b32_e32 v0, 3, v3
	v_sub_u32_e32 v16, 0x80, v120
	v_add3_u32 v121, 0, v15, v14
	v_mul_i32_i24_e32 v15, -4, v3
	v_cmp_eq_u32_e64 s[6:7], 0, v3
	v_lshlrev_b32_e32 v5, 7, v5
	v_lshl_or_b32 v124, v3, 2, v10
	v_mul_lo_u32 v2, v106, s8
	v_add_u32_e32 v3, 0x2200, v131
	v_add3_u32 v1, v1, v14, 0
	v_lshl_add_u64 v[118:119], s[18:19], 0, v[108:109]
	v_cvt_f32_ubyte0_e32 v123, v16
	v_ashrrev_i32_e32 v125, 31, v10
	v_add3_u32 v132, v15, v9, v4
	v_add_u32_e32 v133, 0x4800, v1
	v_add_u32_e32 v134, v7, v2
	v_add_u32_e32 v135, v8, v2
	v_add_u32_e32 v136, v105, v3
	s_mov_b32 s3, 0x3fb8aa3b
	s_mov_b32 s42, 0xc2ce8ed0
	s_mov_b32 s43, 0x42b17218
	v_lshlrev_b32_e32 v108, 1, v0
	v_add_u32_e32 v137, v13, v14
	s_mov_b32 s22, 0xbfb8aa3b
	v_add_u32_e32 v138, v11, v14
	v_add_u32_e32 v139, v6, v5
	v_mov_b32_e32 v140, 0x358637bd
	s_mov_b32 s44, 0x800000
	v_mov_b32_e32 v141, 0x7f800000
	s_mov_b32 s8, s2
	s_branch .LBB0_865

.LBB0_920:
	s_or_b64 exec, exec, s[22:23]
	s_mov_b64 s[22:23], exec
	v_mbcnt_lo_u32_b32 v0, s22, 0
	v_mbcnt_hi_u32_b32 v0, s23, v0
	v_cmp_eq_u32_e32 vcc, 0, v0
	s_and_saveexec_b64 s[34:35], vcc
	s_cbranch_execz .LBB0_922
	s_bcnt1_i32_b64 s3, s[22:23]
	v_mov_b32_e32 v0, 0x2000
	v_mov_b32_e32 v1, s3
	global_atomic_add v0, v1, s[6:7] offset:1024
.LBB0_922:
	s_or_b64 exec, exec, s[34:35]
.LBB0_923:
	s_or_b64 exec, exec, s[0:1]
	s_waitcnt lgkmcnt(0)
	s_barrier
	v_mbcnt_lo_u32_b32 v0, -1, 0
	v_mbcnt_hi_u32_b32 v0, -1, v0
	s_and_b64 vcc, exec, s[4:5]
	v_add_u32_e32 v8, s33, v0
	s_nop 0
	v_readfirstlane_b32 s34, v8
	s_cbranch_vccnz .LBB0_947
	s_ashr_i32 s3, s2, 31
	s_lshr_b32 s0, s3, 29
	s_add_i32 s7, s2, s0
	s_and_b32 s0, s7, -8
	s_sub_i32 s8, s2, s0
	s_cmp_gt_i32 s8, -1
	s_cbranch_scc0 .LBB0_926
	s_lshl_b32 s6, s8, 5
	s_cbranch_execz .LBB0_927
	s_branch .LBB0_928

.LBB0_1020:
	s_or_b64 exec, exec, s[20:21]
	s_mov_b64 s[20:21], exec
	v_mbcnt_lo_u32_b32 v0, s20, 0
	v_mbcnt_hi_u32_b32 v0, s21, v0
	v_cmp_eq_u32_e32 vcc, 0, v0
	s_and_saveexec_b64 s[22:23], vcc
	s_cbranch_execz .LBB0_1022
	s_bcnt1_i32_b64 s3, s[20:21]
	v_mov_b32_e32 v0, 0x2000
	v_mov_b32_e32 v1, s3
	global_atomic_add v0, v1, s[6:7] offset:1024
.LBB0_1022:
	s_or_b64 exec, exec, s[22:23]
.LBB0_1023:
	s_or_b64 exec, exec, s[0:1]
	s_waitcnt lgkmcnt(0)
	s_barrier
	v_mbcnt_lo_u32_b32 v0, -1, 0
	v_mbcnt_hi_u32_b32 v0, -1, v0
	s_andn2_b64 vcc, exec, s[14:15]
	v_add_u32_e32 v8, s33, v0
	v_cndmask_b32_e64 v0, 0, 1, s[14:15]
	v_cmp_ne_u32_e64 s[0:1], 1, v0
	v_readfirstlane_b32 s8, v8
	s_cbranch_vccnz .LBB0_1029
	s_ashr_i32 s3, s2, 31
	s_lshr_b32 s3, s3, 29
	s_add_i32 s3, s2, s3
	s_and_b32 s6, s3, -8
	s_sub_i32 s9, s2, s6
	s_cmp_gt_i32 s9, -1
	s_cbranch_scc0 .LBB0_1026
	s_lshl_b32 s14, s9, 6
	s_cbranch_execz .LBB0_1027
	s_branch .LBB0_1028

.LBB0_1128:
	s_or_b64 exec, exec, s[14:15]
	s_mov_b64 s[14:15], exec
	v_mbcnt_lo_u32_b32 v0, s14, 0
	v_mbcnt_hi_u32_b32 v0, s15, v0
	v_cmp_eq_u32_e32 vcc, 0, v0
	s_and_saveexec_b64 s[18:19], vcc
	s_cbranch_execz .LBB0_1130
	s_bcnt1_i32_b64 s3, s[14:15]
	v_mov_b32_e32 v0, 0x2000
	v_mov_b32_e32 v1, s3
	global_atomic_add v0, v1, s[6:7] offset:1024
.LBB0_1130:
	s_or_b64 exec, exec, s[18:19]
.LBB0_1131:
	s_or_b64 exec, exec, s[0:1]
	s_waitcnt lgkmcnt(0)
	s_barrier
	v_mbcnt_lo_u32_b32 v0, -1, 0
	v_mbcnt_hi_u32_b32 v0, -1, v0
	s_and_b64 vcc, exec, s[4:5]
	v_add_u32_e32 v8, s33, v0
	s_nop 0
	v_readfirstlane_b32 s6, v8
	s_cbranch_vccnz .LBB0_1137
	s_ashr_i32 s0, s2, 31
	s_lshr_b32 s0, s0, 29
	s_add_i32 s3, s2, s0
	s_and_b32 s0, s3, -8
	s_sub_i32 s7, s2, s0
	s_cmp_gt_i32 s7, -1
	s_cbranch_scc0 .LBB0_1134
	s_lshl_b32 s8, s7, 5
	s_cbranch_execz .LBB0_1135
	s_branch .LBB0_1136

.LBB0_1222:
	s_or_b64 exec, exec, s[16:17]
	s_mov_b64 s[16:17], exec
	v_mbcnt_lo_u32_b32 v0, s16, 0
	v_mbcnt_hi_u32_b32 v0, s17, v0
	v_cmp_eq_u32_e32 vcc, 0, v0
	s_and_saveexec_b64 s[18:19], vcc
	s_cbranch_execz .LBB0_1224
	s_bcnt1_i32_b64 s3, s[16:17]
	v_mov_b32_e32 v0, 0x2000
	v_mov_b32_e32 v1, s3
	global_atomic_add v0, v1, s[6:7] offset:1024
.LBB0_1224:
	s_or_b64 exec, exec, s[18:19]
.LBB0_1225:
	s_or_b64 exec, exec, s[0:1]
	s_waitcnt lgkmcnt(0)
	s_barrier
	v_mbcnt_lo_u32_b32 v0, -1, 0
	v_mbcnt_hi_u32_b32 v0, -1, v0
	s_cmpk_gt_i32 s2, 0x57f
	v_add_u32_e32 v9, s33, v0
	s_nop 0
	v_readfirstlane_b32 s7, v9
	s_cbranch_scc1 .LBB0_1241
	v_lshlrev_b32_e32 v0, 4, v9
	v_add_u32_e32 v1, 0x2000, v0
	v_ashrrev_i32_e32 v2, 31, v1
	v_lshrrev_b32_e32 v2, 22, v2
	v_add_u32_e32 v2, v1, v2
	v_ashrrev_i32_e32 v8, 10, v2
	v_mul_i32_i24_e32 v2, 0x400, v8
	v_sub_u32_e32 v1, v1, v2
	v_lshrrev_b32_e32 v2, 4, v1
	v_bitop3_b32 v1, v2, v1, 32 bitop3:0x6c
	v_ashrrev_i32_e32 v2, 31, v1
	v_lshrrev_b32_e32 v2, 26, v2
	v_add_u32_e32 v2, v1, v2
	v_lshlrev_b32_e32 v3, 3, v8
	v_ashrrev_i32_e32 v10, 6, v2
	v_and_b32_e32 v3, -16, v3
	v_add_u32_e32 v3, v10, v3
	v_and_b32_e32 v4, 3, v10
	s_mov_b32 s0, 0x1fffe0
	v_lshrrev_b32_e32 v5, 2, v3
	v_lshlrev_b32_e32 v6, 1, v3
	v_and_b32_e32 v2, 0xc0, v2
	v_and_or_b32 v4, v3, s0, v4
	v_and_b32_e32 v5, 4, v5
	v_and_b32_e32 v6, 24, v6
	v_sub_u32_e32 v1, v1, v2
	v_mov_b32_e32 v2, 1
	v_or3_b32 v4, v4, v5, v6
	v_lshlrev_b32_e32 v5, 5, v8
	v_ashrrev_i16_sdwa v1, v2, sext(v1) dst_sel:DWORD dst_unused:UNUSED_PAD src0_sel:DWORD src1_sel:BYTE_0
	v_and_b32_e32 v5, 32, v5
	v_bfe_i32 v11, v1, 0, 16
	v_add_lshl_u32 v1, v5, v11, 1
	v_lshl_add_u32 v128, v4, 11, v1
	v_lshl_add_u32 v130, v3, 11, v1
	v_bfe_i32 v1, v9, 27, 1
	v_lshrrev_b32_e32 v1, 22, v1
	v_add_u32_e32 v1, v0, v1
	v_and_b32_e32 v1, 0xfffffc00, v1
	v_sub_u32_e32 v0, v0, v1
	v_lshrrev_b32_e32 v1, 4, v0
	v_ashrrev_i32_e32 v3, 31, v9
	v_bitop3_b32 v0, v1, v0, 32 bitop3:0x6c
	v_lshrrev_b32_e32 v3, 26, v3
	v_ashrrev_i32_e32 v1, 31, v0
	v_add_u32_e32 v3, v9, v3
	v_lshrrev_b32_e32 v1, 26, v1
	v_ashrrev_i32_e32 v13, 6, v3
	v_add_u32_e32 v1, v0, v1
	v_lshlrev_b32_e32 v3, 3, v13
	s_add_u32 s3, s26, 0xb00000
	v_ashrrev_i32_e32 v12, 6, v1
	v_and_b32_e32 v3, -16, v3
	s_addc_u32 s46, s27, 0
	v_add_u32_e32 v3, v12, v3
	v_and_b32_e32 v4, 3, v12
	s_ashr_i32 s48, s2, 31
	v_and_or_b32 v4, v3, s0, v4
	s_lshr_b32 s0, s48, 29
	s_add_i32 s0, s2, s0
	s_ashr_i32 s8, s7, 6
	s_ashr_i32 s1, s0, 3
	s_and_b32 s0, s0, -8
	s_ashr_i32 s9, s7, 8
	s_lshl_b32 s47, s8, 10
	s_sub_i32 s0, s2, s0
	s_cmp_lt_i32 s0, 0
	s_movk_i32 s49, 0xb1
	s_cselect_b32 s6, s49, 0xb0
	s_mul_i32 s0, s0, s6
	s_add_i32 s0, s0, s1
	s_mul_hi_i32 s1, s0, 0x2e8ba2e9
	s_lshr_b32 s6, s1, 31
	s_ashr_i32 s1, s1, 4
	s_add_i32 s1, s1, s6
	s_lshl_b32 s16, s1, 2
	s_mulk_i32 s1, 0x58
	s_sub_i32 s0, s0, s1
	s_bfe_i32 s1, s0, 0x80000
	s_bfe_u32 s1, s1, 0x2000d
	s_add_i32 s1, s0, s1
	s_bfe_i32 s6, s1, 0x80000
	s_and_b32 s1, s1, 0xfc
	s_sub_i32 s0, s0, s1
	s_sext_i32_i16 s6, s6
	s_sext_i32_i8 s0, s0
	v_lshrrev_b32_e32 v5, 2, v3
	v_lshlrev_b32_e32 v6, 1, v3
	v_and_b32_e32 v1, 0xc0, v1
	s_lshr_b32 s6, s6, 2
	s_add_i32 s38, s16, s0
	v_and_b32_e32 v5, 4, v5
	v_and_b32_e32 v6, 24, v6
	v_sub_u32_e32 v0, v0, v1
	s_ashr_i32 s39, s38, 31
	s_bfe_i64 s[16:17], s[6:7], 0x100000
	v_or3_b32 v4, v4, v5, v6
	v_lshlrev_b32_e32 v5, 5, v13
	v_ashrrev_i16_sdwa v0, v2, sext(v0) dst_sel:DWORD dst_unused:UNUSED_PAD src0_sel:DWORD src1_sel:BYTE_0
	s_lshl_b64 s[0:1], s[38:39], 19
	s_lshl_b64 s[16:17], s[16:17], 19
	v_and_b32_e32 v5, 32, v5
	v_bfe_i32 v14, v0, 0, 16
	s_add_u32 s42, s3, s16
	v_add_lshl_u32 v0, v5, v14, 1
	s_addc_u32 s43, s46, s17
	s_add_i32 s39, s47, 0
	v_lshl_add_u32 v132, v4, 11, v0
	s_add_i32 m0, s39, 0x10000
	v_lshl_add_u32 v134, v3, 11, v0
	global_load_lds_dwordx4 v132, s[42:43]
	s_add_i32 m0, s39, 0x12000
	s_add_u32 s16, s42, 0x40000
	global_load_lds_dwordx4 v128, s[42:43]
	s_addc_u32 s17, s43, 0
	s_add_i32 m0, s39, 0x14000
	v_mov_b32_e32 v133, 0
	global_load_lds_dwordx4 v132, s[16:17]
	s_add_i32 m0, s39, 0x16000
	s_add_u32 s40, s10, s0
	s_addc_u32 s41, s11, s1
	s_add_i32 s50, s39, 0x2000
	global_load_lds_dwordx4 v128, s[16:17]
	s_mov_b32 m0, s39
	s_add_u32 s0, s40, 0x40000
	global_load_lds_dwordx4 v134, s[40:41]
	s_mov_b32 m0, s50
	s_addc_u32 s1, s41, 0
	s_add_i32 s51, s39, 0x4000
	global_load_lds_dwordx4 v130, s[40:41]
	s_mov_b32 m0, s51
	s_add_i32 s52, s39, 0x6000
	global_load_lds_dwordx4 v134, s[0:1]
	s_mov_b32 m0, s52
	v_mov_b32_e32 v129, v133
	global_load_lds_dwordx4 v130, s[0:1]
	v_mov_b32_e32 v135, v133
	v_mov_b32_e32 v131, v133
	s_cmp_eq_u32 s9, 1
	s_mov_b32 s53, 0
	v_lshl_add_u64 v[6:7], s[42:43], 0, v[132:133]
	v_lshl_add_u64 v[4:5], s[42:43], 0, v[128:129]
	v_lshl_add_u64 v[0:1], s[40:41], 0, v[134:135]
	s_cselect_b64 s[0:1], -1, 0
	s_cmp_lg_u32 s9, 1
	v_lshl_add_u64 v[2:3], s[40:41], 0, v[130:131]
	s_cbranch_scc1 .LBB0_1228
	s_barrier

.LBB0_1290:
	s_or_b64 exec, exec, s[8:9]
	s_mov_b64 s[8:9], exec
	v_mbcnt_lo_u32_b32 v0, s8, 0
	v_mbcnt_hi_u32_b32 v0, s9, v0
	v_cmp_eq_u32_e32 vcc, 0, v0
	s_and_saveexec_b64 s[14:15], vcc
	s_cbranch_execz .LBB0_1292
	s_bcnt1_i32_b64 s3, s[8:9]
	v_mov_b32_e32 v0, 0x2000
	v_mov_b32_e32 v1, s3
	global_atomic_add v0, v1, s[6:7] offset:1024
.LBB0_1292:
	s_or_b64 exec, exec, s[14:15]
.LBB0_1293:
	s_or_b64 exec, exec, s[0:1]
	s_waitcnt lgkmcnt(0)
	s_barrier
	v_mbcnt_lo_u32_b32 v0, -1, 0
	v_mbcnt_hi_u32_b32 v0, -1, v0
	s_and_b64 vcc, exec, s[4:5]
	v_add_u32_e32 v8, s33, v0
	s_nop 0
	v_readfirstlane_b32 s4, v8
	s_cbranch_vccnz .LBB0_1321
	s_ashr_i32 s3, s2, 31
	s_lshr_b32 s0, s3, 29
	s_add_i32 s6, s2, s0
	s_and_b32 s0, s6, -8
	s_sub_i32 s7, s2, s0
	s_cmp_gt_i32 s7, -1
	s_cbranch_scc0 .LBB0_1296
	s_lshl_b32 s5, s7, 5
	s_ashr_i32 s6, s6, 3
	s_cbranch_execz .LBB0_1297
	s_branch .LBB0_1298
